# tile groups start P3 with small staggered offsets (they no longer re-synchronise after P2), so memory-bound epilogues of different groups overlap other groups' K-loops
# speedup vs baseline: 1.0165x; 1.0075x over previous
; #define LAS __attribute__((address_space(3)))
; __device__ __forceinline__ bool attn_unit(const Ptrs& P, LAS unsigned char* lds, int unit, int tid, int wave, int lane, bool pre, int nxt) {
;     const int n = unit & 31, kh = (unit >> 5) & 3, b = unit >> 7;
;     const int g = wave & 3, q0 = 64 * (wave >> 2), h = kh * 4 + g, r = lane & 31, hh = lane >> 5;
;     unsigned char* ws = P.ws;
;     bf16_t* Qb = (bf16_t*)(ws + WS_Q) + (size_t)(b * SEQ + n * 128 + q0) * DM + h * 64;
;     const bf16_t* Kg = (const bf16_t*)(ws + WS_K) + (size_t)b * SEQ * KVW + kh * 64; const bf16_t* Vg = (const bf16_t*)(ws + WS_VT) + (size_t)(b * 4 + kh) * 64 * SEQ;
;     const bf16_t* Kcg = (const bf16_t*)(ws + WS_KC) + (size_t)b * CTX * KVW + kh * 64; const bf16_t* Vcg = (const bf16_t*)(ws + WS_VCT) + (size_t)(b * 4 + kh) * 64 * CTX;
;     float mq = fabsf(P.qg[lane]), mk = fabsf(P.kg[lane]);
; #pragma unroll
;     for (int o = 1; o < 64; o <<= 1) { mq = fmaxf(mq, __shfl_xor(mq, o)); mk = fmaxf(mk, __shfl_xor(mk, o)); }
;     const float sink2 = P.sink[h] * LOG2E; const float mshift = fmaxf(64.0f * QSCALE * mq * mk, sink2);
;     bf16x8_t qf[2][4];
; #pragma unroll
;     for (int cb = 0; cb < 2; ++cb)
; #pragma unroll
;         for (int ds = 0; ds < 4; ++ds) qf[cb][ds] = __builtin_nontemporal_load((const bf16x8_t*)(Qb + (size_t)(32 * cb + r) * DM + 16 * ds + 8 * hh));
;     f32x16 o[2][2];
; #pragma unroll
;     for (int db = 0; db < 2; ++db)
; #pragma unroll
;         for (int cb = 0; cb < 2; ++cb)
; #pragma unroll
;             for (int i = 0; i < 16; ++i) o[db][cb][i] = 0.f;
;     float rs[2] = {0.f, 0.f};
;     f32x16 negm;
; #pragma unroll
;     for (int i = 0; i < 16; ++i) negm[i] = -mshift;
; __device__ __forceinline__ void mk_p3(const Ptrs& P, LAS unsigned char* lds, int tid, int wave, int lane, int bx, int G, bool dry) {
;     ...
;         { bool pre = false; for (int u = bx; u < NB * 32 * 4; u += G) pre = attn_unit(P, lds, u, tid, wave, lane, pre, u + G < NB * 32 * 4 ? u + G : -1); }
.LBB9_305:
	s_cmp_lt_i32 s92, 4
	s_cselect_b64 s[2:3], -1, 0
	s_and_b64 s[22:23], s[2:3], s[0:1]
	s_andn2_b64 vcc, exec, s[22:23]
	s_cbranch_vccnz .LBB9_444
	v_writelane_b32 v251, s22, 33
	s_cmpk_gt_i32 s97, 0x1ff
	v_and_b32_e32 v171, 31, v208
	v_writelane_b32 v251, s23, 34
	v_writelane_b32 v251, s80, 35
	v_lshrrev_b32_e32 v184, 5, v170
	s_nop 0
	v_writelane_b32 v251, s81, 36
	v_writelane_b32 v251, s96, 37
	v_writelane_b32 v251, s83, 38
	v_writelane_b32 v251, s97, 39
	s_cbranch_scc1 .LBB9_413
	v_mbcnt_lo_u32_b32 v0, -1, 0
	v_mbcnt_hi_u32_b32 v0, -1, v0
	v_and_b32_e32 v1, 64, v0
	v_add_u32_e32 v1, 64, v1
	v_xor_b32_e32 v2, 1, v0
	v_cmp_lt_i32_e32 vcc, v2, v1
	s_bfe_u32 s0, s40, 0x20006
	v_writelane_b32 v251, s0, 40
	v_cndmask_b32_e32 v2, v0, v2, vcc
	v_lshlrev_b32_e32 v185, 2, v2
	v_xor_b32_e32 v2, 2, v0
	v_cmp_lt_i32_e32 vcc, v2, v1
	s_lshl_b32 s0, s50, 4
	s_and_b32 s33, s0, 0x3fffffc0
	v_cndmask_b32_e32 v2, v0, v2, vcc
	v_lshlrev_b32_e32 v186, 2, v2
	v_xor_b32_e32 v2, 4, v0
	v_cmp_lt_i32_e32 vcc, v2, v1
	s_cmpk_lt_u32 s40, 0x8c0
	s_cselect_b64 s[54:55], -1, 0
	v_cndmask_b32_e32 v2, v0, v2, vcc
	v_lshlrev_b32_e32 v187, 2, v2
	v_xor_b32_e32 v2, 8, v0
	v_cmp_lt_i32_e32 vcc, v2, v1
	s_or_b32 s2, s0, 63
	s_or_b32 s3, s33, 32
	v_cndmask_b32_e32 v2, v0, v2, vcc
	v_lshlrev_b32_e32 v188, 2, v2
	v_xor_b32_e32 v2, 16, v0
	v_cmp_lt_i32_e32 vcc, v2, v1
	v_or_b32_e32 v5, 32, v170
	v_lshlrev_b32_e32 v191, 4, v184
	v_cndmask_b32_e32 v2, v0, v2, vcc
	v_lshlrev_b32_e32 v189, 2, v2
	v_xor_b32_e32 v2, 32, v0
	v_cmp_lt_i32_e32 vcc, v2, v1
	v_mov_b32_e32 v1, 0
	v_mul_u32_u24_e32 v6, 0x110, v5
	v_cndmask_b32_e32 v0, v0, v2, vcc
	v_lshlrev_b32_e32 v190, 2, v0
	v_lshlrev_b32_e32 v0, 2, v184
	v_sub_u32_e32 v0, v171, v0
	v_cmp_lt_i32_e64 s[36:37], 10, v0
	v_cmp_gt_i32_e64 s[0:1], 1, v0
	v_cmp_gt_i32_e64 s[4:5], 2, v0
	v_writelane_b32 v251, s36, 41
	v_cmp_gt_i32_e64 s[6:7], 3, v0
	v_cmp_gt_i32_e64 s[8:9], 4, v0
	v_writelane_b32 v251, s37, 42
	v_cmp_lt_i32_e64 s[36:37], 15, v0
	v_cmp_gt_i32_e64 s[10:11], 9, v0
	v_cmp_gt_i32_e64 s[12:13], 10, v0
	v_writelane_b32 v251, s36, 43
	v_cmp_gt_i32_e64 s[14:15], 11, v0
	v_cmp_gt_i32_e64 s[16:17], 12, v0
	v_writelane_b32 v251, s37, 44
	v_cmp_lt_i32_e64 s[36:37], 16, v0
	v_cmp_gt_i32_e64 s[18:19], 17, v0
	v_cmp_gt_i32_e64 s[20:21], 18, v0
	v_writelane_b32 v251, s36, 45
	v_cmp_gt_i32_e64 s[22:23], 19, v0
	v_cmp_gt_i32_e64 s[24:25], 20, v0
	v_writelane_b32 v251, s37, 46
	v_cmp_lt_i32_e64 s[36:37], 17, v0
	v_cmp_gt_i32_e64 s[26:27], 25, v0
	v_cmp_gt_i32_e64 s[28:29], 26, v0
	v_writelane_b32 v251, s36, 47
	v_cmp_gt_i32_e64 s[30:31], 27, v0
	v_cmp_gt_i32_e64 s[34:35], 28, v0
	v_writelane_b32 v251, s37, 48
	v_cmp_lt_i32_e64 s[36:37], 18, v0
	v_cmp_lt_i32_e64 s[56:57], -1, v0
	v_cmp_lt_i32_e64 s[86:87], 0, v0
	v_writelane_b32 v251, s36, 49
	v_cmp_lt_i32_e64 s[60:61], 1, v0
	v_cmp_lt_i32_e64 s[62:63], 2, v0
	v_writelane_b32 v251, s37, 50
	v_cmp_lt_i32_e64 s[36:37], 23, v0
	v_cmp_lt_i32_e64 s[64:65], 7, v0
	v_cmp_lt_i32_e64 s[66:67], 8, v0
	v_writelane_b32 v251, s36, 51
	v_cmp_lt_i32_e64 s[72:73], 9, v0
	v_lshlrev_b32_e32 v4, 3, v184
	v_writelane_b32 v251, s37, 52
	v_cmp_lt_i32_e64 s[36:37], 24, v0
	v_mul_u32_u24_e32 v3, 0x110, v171
	v_lshlrev_b32_e32 v2, 10, v171
	v_writelane_b32 v251, s36, 53
	s_movk_i32 s52, 0x110
	v_add3_u32 v3, v3, v191, 0
	v_writelane_b32 v251, s37, 54
	v_cmp_lt_i32_e64 s[36:37], 25, v0
	v_lshlrev_b32_e32 v176, 1, v4
	s_mov_b32 s77, 0
	v_writelane_b32 v251, s36, 55
	v_add_u32_e32 v195, 0x4800, v3
	v_add_u32_e32 v198, 0xd400, v3
	v_writelane_b32 v251, s37, 56
	v_cmp_lt_i32_e64 s[36:37], 26, v0
	v_lshlrev_b32_e32 v0, 2, v170
	v_mad_u32_u24 v200, v5, s52, 0
	v_writelane_b32 v251, s36, 57
	v_mad_u32_u24 v201, v171, s52, 0
	s_mov_b64 s[68:69], 0
	v_writelane_b32 v251, s37, 58
	s_add_u32 s36, s90, 0x6200000
	v_writelane_b32 v251, s36, 59
	s_addc_u32 s36, s91, 0
	v_writelane_b32 v251, s36, 60
	s_add_u32 s36, s90, 0x7200000
	v_writelane_b32 v251, s36, 61
	s_addc_u32 s36, s91, 0
	v_writelane_b32 v251, s36, 62
	v_mov_b32_e32 v178, v176
	v_readlane_b32 s36, v251, 16
	s_add_u32 s36, s90, 0x4200000
	v_readlane_b32 s37, v251, 17
	v_readlane_b32 s38, v251, 18
	v_readlane_b32 s39, v251, 19
	v_readlane_b32 s40, v251, 20
	v_readlane_b32 s41, v251, 21
	v_readlane_b32 s42, v251, 22
	v_readlane_b32 s43, v251, 23
	v_readlane_b32 s44, v251, 24
	v_readlane_b32 s45, v251, 25
	v_readlane_b32 s46, v251, 26
	v_readlane_b32 s47, v251, 27
	v_readlane_b32 s48, v251, 28
	v_readlane_b32 s49, v251, 29
	v_readlane_b32 s50, v251, 30
	v_readlane_b32 s51, v251, 31
	v_writelane_b32 v251, s36, 63
	s_addc_u32 s36, s91, 0
	v_writelane_b32 v250, s36, 0
	s_add_u32 s36, s90, 0x6a00000
	v_writelane_b32 v250, s36, 1
	s_addc_u32 s36, s91, 0
	v_writelane_b32 v250, s36, 2
	s_add_u32 s36, s90, 0x7280000
	v_writelane_b32 v250, s36, 3
	s_addc_u32 s36, s91, 0
	v_writelane_b32 v250, s36, 4
	s_add_u32 s36, s90, 0x2000000
	v_writelane_b32 v250, s36, 5
	s_addc_u32 s36, s91, 0
	v_lshl_add_u64 v[172:173], s[40:41], 0, v[0:1]
	v_writelane_b32 v250, s36, 6
	s_add_i32 s40, 0, 0x11800
	s_add_i32 s76, 0, 0x16000
	v_writelane_b32 v250, s40, 7
	v_writelane_b32 v250, s76, 8
	v_writelane_b32 v250, s88, 9
	v_lshl_add_u64 v[174:175], s[42:43], 0, v[0:1]
	v_readlane_b32 s36, v251, 32
	v_writelane_b32 v250, s89, 10
	v_writelane_b32 v250, s90, 11
	v_writelane_b32 v250, s91, 12
	v_add3_u32 v0, v6, v191, 0
	v_mul_u32_u24_e32 v6, 0x90, v171
	v_writelane_b32 v250, s92, 13
	v_lshl_or_b32 v192, s36, 6, v170
	s_movk_i32 s37, 0x90
	v_add3_u32 v196, v6, v191, 0
	v_writelane_b32 v250, s93, 14
	v_add_u32_e32 v193, 0xfffffb80, v192
	v_add_u32_e32 v194, 0x4800, v0
	v_add_u32_e32 v197, 0xd400, v0
	v_add_u32_e32 v199, 0x8c00, v196
	v_mad_u32_u24 v202, v171, s37, 0
	v_mov_b32_e32 v179, v1
	v_lshlrev_b32_e32 v180, 1, v2
	v_mov_b32_e32 v181, v1
	s_mov_b32 s36, 0xf0f0f0f1
	s_movk_i32 s37, 0xffef
	s_movk_i32 s38, 0x490
	s_mov_b32 s39, 0x38e38e39
	v_readlane_b32 s42, v251, 39
	v_writelane_b32 v250, s94, 22
	v_writelane_b32 v250, s94, 23
	v_mov_b32_e32 v254, 0x24008
	ds_read_b32 v254, v254
	s_waitcnt lgkmcnt(0)
	v_readfirstlane_b32 s98, v254
	s_nop 3
	s_cmp_eq_u32 s98, 1
	s_cbranch_scc0 .Lrm_a
	s_cmpk_lg_i32 s94, 0x100
	s_cbranch_scc1 .Lrm_a
	s_and_b32 s98, s42, 7
	s_lshl_b32 s98, s98, 3
	s_bfe_u32 s99, s42, 0x30003
	s_or_b32 s98, s98, s99
	s_and_b32 vcc_lo, s98, 7
	s_lshl_b32 vcc_lo, vcc_lo, 3
	s_lshr_b32 vcc_hi, s98, 3
	s_or_b32 vcc_lo, vcc_lo, vcc_hi
.Lstg_loop:
	s_cmp_eq_u32 vcc_lo, 0
	s_cbranch_scc1 .Lstg_done
	s_sleep 4
	s_sub_u32 vcc_lo, vcc_lo, 1
	s_branch .Lstg_loop
.Lstg_done:
	s_lshr_b32 s99, s42, 6
	s_lshl_b32 s99, s99, 5
	s_lshr_b32 s42, s98, 4
	s_lshl_b32 s42, s42, 7
	s_or_b32 s42, s42, s99
	s_and_b32 s98, s98, 15
	s_lshl_b32 s98, s98, 1
	s_or_b32 s42, s42, s98
	s_mov_b32 s98, 1
	s_movk_i32 s99, 0x400
	v_writelane_b32 v250, s98, 22
	v_writelane_b32 v250, s99, 23
